# pooling: boundary passes also through the dwordx4 fast path (per-lane validity masks, exact 1/cnt), original branchy loop no longer used
# speedup vs baseline: 1.0008x; 1.0008x over previous
; __device__ __forceinline__ unsigned cvt_pk_bf16(float lo, float hi) { unsigned r; asm volatile("v_cvt_pk_bf16_f32 %0, %1, %2" : "=v"(r) : "v"(lo), "v"(hi)); return r; }
; #define LAS __attribute__((address_space(3)))
; __device__ __forceinline__ int crow(int r, int hi) { return (r & 3) + 8 * (r >> 2) + 4 * hi; }
; template <bool MERGE> __device__ __forceinline__ void compute_b(LAS unsigned char* lds, const UD& x, unsigned char* ws, unsigned char* dout, int wid, int lane, const u32x4 (&pw)[10], float mx, float lsum) {
;     ...
;     asm volatile("s_waitcnt lgkmcnt(0)" ::: "memory");
; #pragma unroll
;     for (int r = 0; r < 16; ++r) {
;         const int qrow = crow(r, hi); const float rl = __builtin_amdgcn_rcpf(wsf[qrow]);
;         const unsigned a = pg8::cvt_pk_bf16(o[0][r] * rl, o[1][r] * rl);
;         stg[qrow * 64 + r32] = (bf16_t)(a & 0xffffu); stg[qrow * 64 + 32 + r32] = (bf16_t)(a >> 16);
;     }
;     asm volatile("s_waitcnt lgkmcnt(0)" ::: "memory");
;     if (!MERGE) {
;         bf16_t* Ob = o_base(ws, dout, x.br, x.b);
; #pragma unroll
;         for (int i = 0; i < 4; ++i) {
;             const int row = i * 8 + (lane >> 3), ch = lane & 7;
;             const u32x4 v = *(const LAS u32x4*)(stg + row * 64 + ch * 8);
;             *(u32x4*)(Ob + (tokb + (size_t)(t0 + row) * d + cls) * AW + x.h * HD + ch * 8) = v;
;         }
;     } else {
;         const float* ST = (const float*)(ws + WS_STAT); bf16_t* MIX = (bf16_t*)(ws + WS_MIXN);
; #pragma unroll
;         for (int i0 = 0; i0 < 4; i0 += 2) {
;             u32x4 o1[2], o2[2]; float m1[2], l1[2], m2[2], l2[2];
; #pragma unroll
;             for (int ii = 0; ii < 2; ++ii) {
;                 const int row = (i0 + ii) * 8 + (lane >> 3), ch = lane & 7; const size_t tok = tokb + (size_t)(t0 + row);
;                 const float* s1 = ST + (((size_t)1 * M + tok) * NH + x.h) * 2; const float* s2 = ST + (((size_t)2 * M + tok) * NH + x.h) * 2;
;                 m1[ii] = s1[0]; l1[ii] = s1[1]; m2[ii] = s2[0]; l2[ii] = s2[1];
;                 o1[ii] = *(const u32x4*)(o_base(ws, dout, 1, x.b) + tok * AW + x.h * HD + ch * 8); o2[ii] = *(const u32x4*)(o_base(ws, dout, 2, x.b) + tok * AW + x.h * HD + ch * 8);
;             }
.LBB0_940:
	s_or_b64 exec, exec, s[18:19]
	s_waitcnt lgkmcnt(0)
	ds_read_b32 v32, v162
	ds_read_b32 v33, v162 offset:4
	ds_read_b32 v34, v162 offset:8
	ds_read_b32 v35, v162 offset:12
	ds_read_b32 v36, v162 offset:32
	ds_read_b32 v37, v162 offset:36
	ds_read_b32 v38, v162 offset:40
	ds_read_b32 v39, v162 offset:44
	ds_read_b32 v40, v162 offset:64
	ds_read_b32 v41, v162 offset:68
	ds_read_b32 v42, v162 offset:72
	ds_read_b32 v43, v162 offset:76
	ds_read_b32 v44, v162 offset:96
	ds_read_b32 v45, v162 offset:100
	ds_read_b32 v46, v162 offset:104
	ds_read_b32 v47, v162 offset:108
	s_waitcnt lgkmcnt(0)
	s_ashr_i32 s19, s22, 31
	s_mul_i32 s24, s0, 0x500000
	v_readlane_b32 s46, v254, 59
	s_mul_hi_i32 s23, s0, 0x500000
	v_rcp_f32_e32 v32, v32
	v_readlane_b32 s47, v254, 60
	v_mov_b32_e32 v145, v81
	v_mul_f32_e32 v0, v0, v32
	v_mul_f32_e32 v16, v16, v32
	v_cvt_pk_bf16_f32 v0, v0, v16
	ds_write_b16 v163, v0
	ds_write_b16_d16_hi v164, v0
	v_rcp_f32_e32 v0, v33
	s_nop 0
	v_mul_f32_e32 v1, v1, v0
	v_mul_f32_e32 v0, v17, v0
	v_cvt_pk_bf16_f32 v0, v1, v0
	ds_write_b16 v165, v0
	ds_write_b16_d16_hi v166, v0
	v_rcp_f32_e32 v0, v34
	s_nop 0
	v_mul_f32_e32 v1, v2, v0
	v_mul_f32_e32 v0, v18, v0
	v_cvt_pk_bf16_f32 v0, v1, v0
	ds_write_b16 v167, v0
	ds_write_b16_d16_hi v168, v0
	v_rcp_f32_e32 v0, v35
	s_nop 0
	v_mul_f32_e32 v1, v3, v0
	v_mul_f32_e32 v0, v19, v0
	v_cvt_pk_bf16_f32 v0, v1, v0
	ds_write_b16 v169, v0
	ds_write_b16_d16_hi v170, v0
	v_rcp_f32_e32 v0, v36
	s_nop 0
	v_mul_f32_e32 v1, v4, v0
	v_mul_f32_e32 v0, v20, v0
	v_cvt_pk_bf16_f32 v0, v1, v0
	ds_write_b16 v171, v0
	ds_write_b16_d16_hi v172, v0
	v_rcp_f32_e32 v0, v37
	s_nop 0
	v_mul_f32_e32 v1, v5, v0
	v_mul_f32_e32 v0, v21, v0
	v_cvt_pk_bf16_f32 v0, v1, v0
	ds_write_b16 v173, v0
	ds_write_b16_d16_hi v174, v0
	v_rcp_f32_e32 v0, v38
	s_nop 0
	v_mul_f32_e32 v1, v6, v0
	v_mul_f32_e32 v0, v22, v0
	v_cvt_pk_bf16_f32 v0, v1, v0
	ds_write_b16 v175, v0
	ds_write_b16_d16_hi v176, v0
	v_rcp_f32_e32 v0, v39
	s_nop 0
	v_mul_f32_e32 v1, v7, v0
	v_mul_f32_e32 v0, v23, v0
	v_cvt_pk_bf16_f32 v0, v1, v0
	ds_write_b16 v177, v0
	ds_write_b16_d16_hi v178, v0
	v_rcp_f32_e32 v0, v40
	s_nop 0
	v_mul_f32_e32 v1, v8, v0
	v_mul_f32_e32 v0, v24, v0
	v_cvt_pk_bf16_f32 v0, v1, v0
	ds_write_b16 v179, v0
	ds_write_b16_d16_hi v180, v0
	v_rcp_f32_e32 v0, v41
	s_nop 0
	v_mul_f32_e32 v1, v9, v0
	v_mul_f32_e32 v0, v25, v0
	v_cvt_pk_bf16_f32 v0, v1, v0
	ds_write_b16 v181, v0
	ds_write_b16_d16_hi v182, v0
	v_rcp_f32_e32 v0, v42
	s_nop 0
	v_mul_f32_e32 v1, v10, v0
	v_mul_f32_e32 v0, v26, v0
	v_cvt_pk_bf16_f32 v0, v1, v0
	ds_write_b16 v183, v0
	ds_write_b16_d16_hi v184, v0
	v_rcp_f32_e32 v0, v43
	s_nop 0
	v_mul_f32_e32 v1, v11, v0
	v_mul_f32_e32 v0, v27, v0
	v_cvt_pk_bf16_f32 v0, v1, v0
	ds_write_b16 v185, v0
	ds_write_b16_d16_hi v186, v0
	v_rcp_f32_e32 v0, v44
	s_nop 0
	v_mul_f32_e32 v1, v12, v0
	v_mul_f32_e32 v0, v28, v0
	v_cvt_pk_bf16_f32 v0, v1, v0
	ds_write_b16 v187, v0
	ds_write_b16_d16_hi v188, v0
	v_rcp_f32_e32 v0, v45
	s_nop 0
	v_mul_f32_e32 v1, v13, v0
	v_mul_f32_e32 v0, v29, v0
	v_cvt_pk_bf16_f32 v0, v1, v0
	ds_write_b16 v189, v0
	ds_write_b16_d16_hi v202, v0
	v_rcp_f32_e32 v0, v46
	s_nop 0
	v_mul_f32_e32 v1, v14, v0
	v_mul_f32_e32 v0, v30, v0
	v_cvt_pk_bf16_f32 v0, v1, v0
	ds_write_b16 v203, v0
	ds_write_b16_d16_hi v204, v0
	v_or_b32_e32 v14, s20, v207
	s_add_u32 s20, s22, 0x30000
	s_addc_u32 s21, s19, 0
	s_add_u32 s18, s22, 0x60000
	v_rcp_f32_e32 v0, v47
	s_addc_u32 s19, s19, 0
	s_lshl_b64 s[16:17], s[16:17], 1
	s_add_u32 s24, s46, s24
	s_addc_u32 s23, s47, s23
	v_mul_f32_e32 v1, v15, v0
	v_mul_f32_e32 v0, v31, v0
	s_add_u32 s24, s24, s16
	v_ashrrev_i32_e32 v15, 31, v14
	v_cvt_pk_bf16_f32 v0, v1, v0
	s_addc_u32 s25, s23, s17
	v_lshl_add_u64 v[24:25], s[14:15], 0, v[14:15]
	ds_write_b16 v205, v0
	ds_write_b16_d16_hi v206, v0
	v_lshl_add_u64 v[16:17], s[24:25], 0, v[144:145]
	v_mad_u64_u32 v[0:1], s[24:25], v24, 12, s[20:21]
	v_mad_i32_i24 v1, v25, 12, v1
	v_mad_u64_u32 v[2:3], s[24:25], v24, 12, s[18:19]
	s_waitcnt lgkmcnt(0)
	v_lshl_add_u64 v[0:1], v[0:1], 3, s[34:35]
	v_mad_i32_i24 v3, v25, 12, v3
	v_lshl_add_u64 v[2:3], v[2:3], 3, s[34:35]
	global_load_dwordx2 v[34:35], v[0:1], off
	global_load_dwordx2 v[36:37], v[2:3], off
	v_lshl_add_u64 v[12:13], v[136:137], 0, s[16:17]
	v_mad_u64_u32 v[0:1], s[24:25], v24, s40, v[12:13]
	v_mad_i32_i24 v1, v25, s40, v1
	global_load_dwordx4 v[8:11], v[0:1], off
	v_mad_u64_u32 v[0:1], s[24:25], v24, s40, v[16:17]
	v_mad_i32_i24 v1, v25, s40, v1
	global_load_dwordx4 v[26:29], v[0:1], off
	v_or_b32_e32 v0, 8, v14
	v_ashrrev_i32_e32 v1, 31, v0
	v_lshl_add_u64 v[18:19], s[14:15], 0, v[0:1]
	v_mad_u64_u32 v[0:1], s[24:25], v18, 12, s[20:21]
	v_mad_i32_i24 v1, v19, 12, v1
	v_mad_u64_u32 v[2:3], s[24:25], v18, 12, s[18:19]
	v_lshl_add_u64 v[0:1], v[0:1], 3, s[34:35]
	v_mad_i32_i24 v3, v19, 12, v3
	v_lshl_add_u64 v[2:3], v[2:3], 3, s[34:35]
	global_load_dwordx2 v[20:21], v[0:1], off
	global_load_dwordx2 v[22:23], v[2:3], off
	v_mad_u64_u32 v[0:1], s[24:25], v18, s40, v[12:13]
	v_mad_i32_i24 v1, v19, s40, v1
	global_load_dwordx4 v[0:3], v[0:1], off
	v_mad_u64_u32 v[4:5], s[24:25], v18, s40, v[16:17]
	v_mad_i32_i24 v5, v19, s40, v5
	global_load_dwordx4 v[4:7], v[4:5], off
	v_add_u32_e32 v15, v208, v209
	ds_read_b128 v[30:33], v15
	ds_read2_b32 v[38:39], v210 offset1:32
	v_lshlrev_b64 v[24:25], 11, v[24:25]
	v_lshl_add_u64 v[24:25], s[84:85], 0, v[24:25]
	v_lshl_add_u64 v[24:25], v[24:25], 0, s[16:17]
	v_lshl_add_u64 v[24:25], v[24:25], 0, v[144:145]
	s_cmp_gt_i32 s22, 3
	s_waitcnt vmcnt(6) lgkmcnt(0)
; __device__ __forceinline__ unsigned cvt_pk_bf16(float lo, float hi) { unsigned r; asm volatile("v_cvt_pk_bf16_f32 %0, %1, %2" : "=v"(r) : "v"(lo), "v"(hi)); return r; }
; template <bool MERGE> __device__ __forceinline__ void compute_b(LAS unsigned char* lds, const UD& x, unsigned char* ws, unsigned char* dout, int wid, int lane, const u32x4 (&pw)[10], float mx, float lsum) {
;     ...
;             u32x4 o1[2], o2[2]; float m1[2], l1[2], m2[2], l2[2];
; #pragma unroll
;             for (int ii = 0; ii < 2; ++ii) {
;                 const int row = (i0 + ii) * 8 + (lane >> 3), ch = lane & 7; const size_t tok = tokb + (size_t)(t0 + row);
;                 const float* s1 = ST + (((size_t)1 * M + tok) * NH + x.h) * 2; const float* s2 = ST + (((size_t)2 * M + tok) * NH + x.h) * 2;
;                 m1[ii] = s1[0]; l1[ii] = s1[1]; m2[ii] = s2[0]; l2[ii] = s2[1];
;                 o1[ii] = *(const u32x4*)(o_base(ws, dout, 1, x.b) + tok * AW + x.h * HD + ch * 8); o2[ii] = *(const u32x4*)(o_base(ws, dout, 2, x.b) + tok * AW + x.h * HD + ch * 8);
;             }
; #pragma unroll
;             for (int ii = 0; ii < 2; ++ii) {
;                 const int row = (i0 + ii) * 8 + (lane >> 3), ch = lane & 7; const size_t tok = tokb + (size_t)(t0 + row);
;                 const u32x4 v0 = *(const LAS u32x4*)(stg + row * 64 + ch * 8);
;                 const float m0 = wsf[32 + row], l0 = wsf[row];
;                 const float mxx = fmaxf(fmaxf(m0, m1[ii]), m2[ii]);
;                 float w0 = __builtin_amdgcn_exp2f(m0 - mxx) * l0, w1 = __builtin_amdgcn_exp2f(m1[ii] - mxx) * l1[ii], w2 = __builtin_amdgcn_exp2f(m2[ii] - mxx) * l2[ii];
;                 const float rd = 1.0f / (w0 + w1 + w2); w0 *= rd; w1 *= rd; w2 *= rd;
;                 const u32x4 a1 = o1[ii], a2 = o2[ii];
;                 u32x4 w;
;                 w.x = pg8::cvt_pk_bf16(w0 * __uint_as_float(v0.x << 16) + w1 * __uint_as_float(a1.x << 16) + w2 * __uint_as_float(a2.x << 16), w0 * __uint_as_float(v0.x & 0xffff0000u) + w1 * __uint_as_float(a1.x & 0xffff0000u) + w2 * __uint_as_float(a2.x & 0xffff0000u));
;                 w.y = pg8::cvt_pk_bf16(w0 * __uint_as_float(v0.y << 16) + w1 * __uint_as_float(a1.y << 16) + w2 * __uint_as_float(a2.y << 16), w0 * __uint_as_float(v0.y & 0xffff0000u) + w1 * __uint_as_float(a1.y & 0xffff0000u) + w2 * __uint_as_float(a2.y & 0xffff0000u));
	v_max3_f32 v15, v39, v34, v36
	v_sub_f32_e32 v39, v39, v15
	v_sub_f32_e32 v34, v34, v15
	v_sub_f32_e32 v15, v36, v15
	v_exp_f32_e32 v41, v39
	v_exp_f32_e32 v40, v15
	v_exp_f32_e32 v34, v34
	s_waitcnt vmcnt(5)
	v_lshlrev_b32_e32 v15, 16, v8
	v_and_b32_e32 v36, 0xffff0000, v8
	v_lshlrev_b32_e32 v42, 16, v9
	v_and_b32_e32 v43, 0xffff0000, v9
	v_mov_b32_e32 v8, v37
	v_mov_b32_e32 v9, v38
	v_pk_mul_f32 v[8:9], v[8:9], v[40:41]
	v_lshlrev_b32_e32 v44, 16, v10
	v_and_b32_e32 v45, 0xffff0000, v10
	v_fma_f32 v10, v35, v34, v9
	v_add_f32_e32 v10, v8, v10
	v_mul_f32_e32 v39, v35, v34
	v_div_scale_f32 v34, s[24:25], v10, v10, 1.0
	v_rcp_f32_e32 v35, v34
	v_lshlrev_b32_e32 v46, 16, v11
	v_fma_f32 v37, -v34, v35, 1.0
	v_fmac_f32_e32 v35, v37, v35
	v_div_scale_f32 v37, vcc, 1.0, v10, 1.0
	v_mul_f32_e32 v38, v37, v35
	v_fma_f32 v40, -v34, v38, v37
	v_fmac_f32_e32 v38, v40, v35
	v_fma_f32 v34, -v34, v38, v37
	v_div_fmas_f32 v34, v34, v35, v38
	v_div_fixup_f32 v10, v34, v10, 1.0
	v_pk_mul_f32 v[34:35], v[8:9], v[10:11] op_sel_hi:[1,0]
	s_waitcnt vmcnt(4)
	v_lshlrev_b32_e32 v8, 16, v26
	v_lshlrev_b32_e32 v9, 16, v30
	v_mul_f32_e32 v38, v39, v10
	v_pk_mul_f32 v[8:9], v[34:35], v[8:9]
	v_lshlrev_b32_e32 v37, 16, v31
	v_fma_f32 v9, v38, v15, v9
	v_add_f32_e32 v10, v8, v9
	v_and_b32_e32 v9, 0xffff0000, v30
	v_and_b32_e32 v8, 0xffff0000, v26
	v_pk_mul_f32 v[8:9], v[34:35], v[8:9]
	v_and_b32_e32 v31, 0xffff0000, v31
	v_fma_f32 v9, v38, v36, v9
	v_and_b32_e32 v30, 0xffff0000, v27
	v_add_f32_e32 v8, v8, v9
	v_lshlrev_b32_e32 v36, 16, v27
	v_pk_mul_f32 v[26:27], v[34:35], v[30:31]
	v_cvt_pk_bf16_f32 v8, v10, v8
	v_pk_mul_f32 v[36:37], v[34:35], v[36:37]
	v_fma_f32 v10, v38, v43, v27
	v_fma_f32 v9, v38, v42, v37
	v_add_f32_e32 v10, v26, v10
	v_lshlrev_b32_e32 v26, 16, v28
	v_lshlrev_b32_e32 v27, 16, v32
	v_add_f32_e32 v9, v36, v9
	v_pk_mul_f32 v[26:27], v[34:35], v[26:27]
	v_cvt_pk_bf16_f32 v9, v9, v10
	v_and_b32_e32 v11, 0xffff0000, v11
	v_fma_f32 v10, v38, v44, v27
	v_add_f32_e32 v10, v26, v10
	v_and_b32_e32 v27, 0xffff0000, v32
	v_and_b32_e32 v26, 0xffff0000, v28
	v_pk_mul_f32 v[26:27], v[34:35], v[26:27]
	s_waitcnt vmcnt(1)
	v_lshlrev_b32_e32 v28, 16, v1
	v_fma_f32 v15, v38, v45, v27
	v_add_f32_e32 v15, v26, v15
	v_lshlrev_b32_e32 v26, 16, v29
	v_lshlrev_b32_e32 v27, 16, v33
	v_pk_mul_f32 v[26:27], v[34:35], v[26:27]
	v_cvt_pk_bf16_f32 v10, v10, v15
	v_lshlrev_b32_e32 v30, 16, v2
	v_fma_f32 v15, v38, v46, v27
	v_add_f32_e32 v15, v26, v15
	v_and_b32_e32 v27, 0xffff0000, v33
	v_and_b32_e32 v26, 0xffff0000, v29
	v_pk_mul_f32 v[26:27], v[34:35], v[26:27]
	v_and_b32_e32 v29, 0xffff0000, v1
	v_fma_f32 v11, v38, v11, v27
	v_add_f32_e32 v11, v26, v11
	v_cvt_pk_bf16_f32 v11, v15, v11
	global_store_dwordx4 v[24:25], v[8:11], off offset:512
	ds_read_b128 v[8:11], v229
	ds_read2_b32 v[26:27], v210 offset0:8 offset1:40
	v_and_b32_e32 v31, 0xffff0000, v2
	v_lshlrev_b32_e32 v32, 16, v3
	s_waitcnt lgkmcnt(0)
	v_max3_f32 v15, v27, v20, v22
	v_sub_f32_e32 v24, v27, v15
	v_sub_f32_e32 v20, v20, v15
	v_sub_f32_e32 v15, v22, v15
	v_exp_f32_e32 v25, v24
	v_exp_f32_e32 v24, v15
	v_exp_f32_e32 v20, v20
	v_lshlrev_b32_e32 v15, 16, v0
	v_and_b32_e32 v22, 0xffff0000, v0
	v_mov_b32_e32 v0, v23
	v_mov_b32_e32 v1, v26
	v_pk_mul_f32 v[0:1], v[0:1], v[24:25]
	v_mul_f32_e32 v27, v21, v20
	v_fma_f32 v2, v21, v20, v1
	v_add_f32_e32 v2, v0, v2
	v_div_scale_f32 v20, s[24:25], v2, v2, 1.0
	v_rcp_f32_e32 v21, v20
	s_nop 0
	v_fma_f32 v23, -v20, v21, 1.0
	v_fmac_f32_e32 v21, v23, v21
	v_div_scale_f32 v23, vcc, 1.0, v2, 1.0
	v_mul_f32_e32 v24, v23, v21
	v_fma_f32 v25, -v20, v24, v23
	v_fmac_f32_e32 v24, v25, v21
	v_fma_f32 v20, -v20, v24, v23
	v_div_fmas_f32 v20, v20, v21, v24
	v_div_fixup_f32 v2, v20, v2, 1.0
	v_pk_mul_f32 v[20:21], v[0:1], v[2:3] op_sel_hi:[1,0]
	s_waitcnt vmcnt(1)
	v_lshlrev_b32_e32 v0, 16, v4
	v_lshlrev_b32_e32 v1, 16, v8
	v_mul_f32_e32 v24, v27, v2
	v_pk_mul_f32 v[0:1], v[20:21], v[0:1]
	v_lshlrev_b32_e32 v23, 16, v9
	v_fma_f32 v1, v24, v15, v1
	v_add_f32_e32 v2, v0, v1
	v_and_b32_e32 v1, 0xffff0000, v8
	v_and_b32_e32 v0, 0xffff0000, v4
	v_pk_mul_f32 v[0:1], v[20:21], v[0:1]
	v_and_b32_e32 v9, 0xffff0000, v9
	v_fma_f32 v1, v24, v22, v1
	v_and_b32_e32 v8, 0xffff0000, v5
	v_add_f32_e32 v0, v0, v1
	v_lshlrev_b32_e32 v22, 16, v5
	v_pk_mul_f32 v[4:5], v[20:21], v[8:9]
	v_cvt_pk_bf16_f32 v0, v2, v0
	v_pk_mul_f32 v[22:23], v[20:21], v[22:23]
	v_fma_f32 v2, v24, v29, v5
	v_fma_f32 v1, v24, v28, v23
	v_add_f32_e32 v2, v4, v2
	v_lshlrev_b32_e32 v4, 16, v6
	v_lshlrev_b32_e32 v5, 16, v10
	v_add_f32_e32 v1, v22, v1
	v_pk_mul_f32 v[4:5], v[20:21], v[4:5]
	v_cvt_pk_bf16_f32 v1, v1, v2
	v_and_b32_e32 v3, 0xffff0000, v3
	v_fma_f32 v2, v24, v30, v5
	v_add_f32_e32 v2, v4, v2
	v_and_b32_e32 v5, 0xffff0000, v10
	v_and_b32_e32 v4, 0xffff0000, v6
	v_pk_mul_f32 v[4:5], v[20:21], v[4:5]
	s_nop 0
	v_fma_f32 v5, v24, v31, v5
	v_add_f32_e32 v4, v4, v5
	v_cvt_pk_bf16_f32 v2, v2, v4
	v_lshlrev_b32_e32 v4, 16, v7
	v_lshlrev_b32_e32 v5, 16, v11
	v_pk_mul_f32 v[4:5], v[20:21], v[4:5]
	s_nop 0
	v_fma_f32 v5, v24, v32, v5
	v_add_f32_e32 v6, v4, v5
	v_and_b32_e32 v5, 0xffff0000, v11
	v_and_b32_e32 v4, 0xffff0000, v7
	v_pk_mul_f32 v[4:5], v[20:21], v[4:5]
	s_nop 0
	v_fma_f32 v3, v24, v3, v5
	v_add_f32_e32 v3, v4, v3
	v_lshlrev_b64 v[4:5], 11, v[18:19]
	v_lshl_add_u64 v[4:5], s[84:85], 0, v[4:5]
	v_lshl_add_u64 v[4:5], v[4:5], 0, s[16:17]
	v_lshl_add_u64 v[4:5], v[4:5], 0, v[144:145]
	v_cvt_pk_bf16_f32 v3, v6, v3
	global_store_dwordx4 v[4:5], v[0:3], off offset:512
	s_nop 1
	v_or_b32_e32 v0, 16, v14
	v_ashrrev_i32_e32 v1, 31, v0
	v_lshl_add_u64 v[30:31], s[14:15], 0, v[0:1]
	v_mad_u64_u32 v[0:1], s[24:25], v30, 12, s[20:21]
	v_mad_i32_i24 v1, v31, 12, v1
	v_mad_u64_u32 v[2:3], s[24:25], v30, 12, s[18:19]
	v_lshl_add_u64 v[0:1], v[0:1], 3, s[34:35]
	v_mad_i32_i24 v3, v31, 12, v3
	v_lshl_add_u64 v[2:3], v[2:3], 3, s[34:35]
	global_load_dwordx2 v[32:33], v[0:1], off
	global_load_dwordx2 v[34:35], v[2:3], off
	v_mad_u64_u32 v[0:1], s[24:25], v30, s40, v[12:13]
	v_mad_i32_i24 v1, v31, s40, v1
	global_load_dwordx4 v[18:21], v[0:1], off
	v_mad_u64_u32 v[0:1], s[24:25], v30, s40, v[16:17]
	v_mad_i32_i24 v1, v31, s40, v1
	global_load_dwordx4 v[22:25], v[0:1], off
	v_or_b32_e32 v0, 24, v14
	v_ashrrev_i32_e32 v1, 31, v0
	v_lshl_add_u64 v[8:9], s[14:15], 0, v[0:1]
	v_mad_u64_u32 v[0:1], s[14:15], v8, 12, s[20:21]
	v_mad_i32_i24 v1, v9, 12, v1
	v_mad_u64_u32 v[2:3], s[14:15], v8, 12, s[18:19]
	v_lshl_add_u64 v[0:1], v[0:1], 3, s[34:35]
	v_mad_i32_i24 v3, v9, 12, v3
	v_lshl_add_u64 v[2:3], v[2:3], 3, s[34:35]
	global_load_dwordx2 v[10:11], v[0:1], off
	global_load_dwordx2 v[14:15], v[2:3], off
	v_mad_u64_u32 v[0:1], s[14:15], v8, s40, v[12:13]
	v_mad_i32_i24 v1, v9, s40, v1
	global_load_dwordx4 v[0:3], v[0:1], off
	v_mad_u64_u32 v[4:5], s[14:15], v8, s40, v[16:17]
	v_mad_i32_i24 v5, v9, s40, v5
	global_load_dwordx4 v[4:7], v[4:5], off
	ds_read_b128 v[26:29], v230
	ds_read2_b32 v[12:13], v210 offset0:16 offset1:48
	s_waitcnt vmcnt(6) lgkmcnt(0)
; __device__ __forceinline__ unsigned cvt_pk_bf16(float lo, float hi) { unsigned r; asm volatile("v_cvt_pk_bf16_f32 %0, %1, %2" : "=v"(r) : "v"(lo), "v"(hi)); return r; }
; #define LAS __attribute__((address_space(3)))
; template <bool MERGE> __device__ __forceinline__ void compute_b(LAS unsigned char* lds, const UD& x, unsigned char* ws, unsigned char* dout, int wid, int lane, const u32x4 (&pw)[10], float mx, float lsum) {
;     ...
; #pragma unroll
;             for (int ii = 0; ii < 2; ++ii) {
;                 const int row = (i0 + ii) * 8 + (lane >> 3), ch = lane & 7; const size_t tok = tokb + (size_t)(t0 + row);
;                 const u32x4 v0 = *(const LAS u32x4*)(stg + row * 64 + ch * 8);
;                 const float m0 = wsf[32 + row], l0 = wsf[row];
;                 const float mxx = fmaxf(fmaxf(m0, m1[ii]), m2[ii]);
;                 float w0 = __builtin_amdgcn_exp2f(m0 - mxx) * l0, w1 = __builtin_amdgcn_exp2f(m1[ii] - mxx) * l1[ii], w2 = __builtin_amdgcn_exp2f(m2[ii] - mxx) * l2[ii];
;                 const float rd = 1.0f / (w0 + w1 + w2); w0 *= rd; w1 *= rd; w2 *= rd;
;                 const u32x4 a1 = o1[ii], a2 = o2[ii];
;                 u32x4 w;
;                 w.x = pg8::cvt_pk_bf16(w0 * __uint_as_float(v0.x << 16) + w1 * __uint_as_float(a1.x << 16) + w2 * __uint_as_float(a2.x << 16), w0 * __uint_as_float(v0.x & 0xffff0000u) + w1 * __uint_as_float(a1.x & 0xffff0000u) + w2 * __uint_as_float(a2.x & 0xffff0000u));
;                 w.y = pg8::cvt_pk_bf16(w0 * __uint_as_float(v0.y << 16) + w1 * __uint_as_float(a1.y << 16) + w2 * __uint_as_float(a2.y << 16), w0 * __uint_as_float(v0.y & 0xffff0000u) + w1 * __uint_as_float(a1.y & 0xffff0000u) + w2 * __uint_as_float(a2.y & 0xffff0000u));
;                 w.z = pg8::cvt_pk_bf16(w0 * __uint_as_float(v0.z << 16) + w1 * __uint_as_float(a1.z << 16) + w2 * __uint_as_float(a2.z << 16), w0 * __uint_as_float(v0.z & 0xffff0000u) + w1 * __uint_as_float(a1.z & 0xffff0000u) + w2 * __uint_as_float(a2.z & 0xffff0000u));
;                 w.w = pg8::cvt_pk_bf16(w0 * __uint_as_float(v0.w << 16) + w1 * __uint_as_float(a1.w << 16) + w2 * __uint_as_float(a2.w << 16), w0 * __uint_as_float(v0.w & 0xffff0000u) + w1 * __uint_as_float(a1.w & 0xffff0000u) + w2 * __uint_as_float(a2.w & 0xffff0000u));
;                 *(u32x4*)(MIX + tok * DM + PWD + x.h * HD + ch * 8) = w;
;             }
;         }
;         if (x.h < 4) {
	v_max3_f32 v16, v13, v32, v34
	v_sub_f32_e32 v13, v13, v16
	v_exp_f32_e32 v17, v13
	v_sub_f32_e32 v13, v32, v16
	v_exp_f32_e32 v32, v13
	v_sub_f32_e32 v13, v34, v16
	v_exp_f32_e32 v16, v13
	s_waitcnt vmcnt(5)
	v_lshlrev_b32_e32 v34, 16, v18
	v_and_b32_e32 v37, 0xffff0000, v18
	v_lshlrev_b32_e32 v38, 16, v19
	v_and_b32_e32 v39, 0xffff0000, v19
	v_mov_b32_e32 v18, v35
	v_mov_b32_e32 v19, v12
	v_pk_mul_f32 v[12:13], v[18:19], v[16:17]
	v_mul_f32_e32 v36, v33, v32
	v_fma_f32 v16, v33, v32, v13
	v_add_f32_e32 v16, v12, v16
	v_div_scale_f32 v17, s[14:15], v16, v16, 1.0
	v_rcp_f32_e32 v18, v17
	v_lshlrev_b32_e32 v40, 16, v20
	v_and_b32_e32 v20, 0xffff0000, v20
	v_lshlrev_b32_e32 v41, 16, v21
	v_fma_f32 v19, -v17, v18, 1.0
	v_fmac_f32_e32 v18, v19, v18
	v_div_scale_f32 v19, vcc, 1.0, v16, 1.0
	v_mul_f32_e32 v32, v19, v18
	v_fma_f32 v33, -v17, v32, v19
	v_fmac_f32_e32 v32, v33, v18
	v_fma_f32 v17, -v17, v32, v19
	v_div_fmas_f32 v17, v17, v18, v32
	v_div_fixup_f32 v16, v17, v16, 1.0
	v_mul_f32_e32 v32, v36, v16
	v_pk_mul_f32 v[12:13], v[12:13], v[16:17] op_sel_hi:[1,0]
	s_waitcnt vmcnt(4)
	v_lshlrev_b32_e32 v16, 16, v22
	v_lshlrev_b32_e32 v17, 16, v26
	v_pk_mul_f32 v[16:17], v[12:13], v[16:17]
	v_lshlrev_b32_e32 v19, 16, v27
	v_fma_f32 v17, v32, v34, v17
	v_add_f32_e32 v18, v16, v17
	v_and_b32_e32 v17, 0xffff0000, v26
	v_and_b32_e32 v16, 0xffff0000, v22
	v_pk_mul_f32 v[16:17], v[12:13], v[16:17]
	s_waitcnt vmcnt(1)
	v_and_b32_e32 v26, 0xffff0000, v2
	v_fma_f32 v17, v32, v37, v17
	v_add_f32_e32 v16, v16, v17
	v_cvt_pk_bf16_f32 v16, v18, v16
	v_lshlrev_b32_e32 v18, 16, v23
	v_pk_mul_f32 v[18:19], v[12:13], v[18:19]
	s_nop 0
	v_fma_f32 v17, v32, v38, v19
	v_add_f32_e32 v17, v18, v17
	v_and_b32_e32 v19, 0xffff0000, v27
	v_and_b32_e32 v18, 0xffff0000, v23
	v_pk_mul_f32 v[18:19], v[12:13], v[18:19]
	v_lshlrev_b32_e32 v23, 16, v29
	v_fma_f32 v19, v32, v39, v19
	v_add_f32_e32 v18, v18, v19
	v_cvt_pk_bf16_f32 v17, v17, v18
	v_lshlrev_b32_e32 v18, 16, v24
	v_lshlrev_b32_e32 v19, 16, v28
	v_pk_mul_f32 v[18:19], v[12:13], v[18:19]
	v_lshlrev_b32_e32 v27, 16, v3
	v_fma_f32 v19, v32, v40, v19
	v_add_f32_e32 v22, v18, v19
	v_and_b32_e32 v19, 0xffff0000, v28
	v_and_b32_e32 v18, 0xffff0000, v24
	v_pk_mul_f32 v[18:19], v[12:13], v[18:19]
	v_and_b32_e32 v24, 0xffff0000, v1
	v_fma_f32 v19, v32, v20, v19
	v_add_f32_e32 v18, v18, v19
	v_cvt_pk_bf16_f32 v18, v22, v18
	v_lshlrev_b32_e32 v22, 16, v25
	v_pk_mul_f32 v[22:23], v[12:13], v[22:23]
	v_and_b32_e32 v20, 0xffff0000, v25
	v_fma_f32 v19, v32, v41, v23
	v_add_f32_e32 v19, v22, v19
	v_and_b32_e32 v22, 0xffff0000, v21
	v_and_b32_e32 v21, 0xffff0000, v29
	v_pk_mul_f32 v[12:13], v[12:13], v[20:21]
	v_lshlrev_b32_e32 v23, 16, v1
	v_fma_f32 v13, v32, v22, v13
	v_add_f32_e32 v12, v12, v13
	v_cvt_pk_bf16_f32 v19, v19, v12
	v_lshlrev_b64 v[12:13], 11, v[30:31]
	v_lshl_add_u64 v[12:13], s[84:85], 0, v[12:13]
	v_lshl_add_u64 v[12:13], v[12:13], 0, s[16:17]
	v_lshl_add_u64 v[12:13], v[12:13], 0, v[144:145]
	global_store_dwordx4 v[12:13], v[16:19], off offset:512
	ds_read_b128 v[16:19], v231
	ds_read2_b32 v[12:13], v210 offset0:24 offset1:56
	v_and_b32_e32 v22, 0xffff0000, v0
	v_lshlrev_b32_e32 v25, 16, v2
	s_waitcnt lgkmcnt(0)
	v_max3_f32 v20, v13, v10, v14
	v_sub_f32_e32 v13, v13, v20
	v_sub_f32_e32 v14, v14, v20
	v_exp_f32_e32 v21, v13
	v_sub_f32_e32 v10, v10, v20
	v_exp_f32_e32 v20, v14
	v_exp_f32_e32 v10, v10
	v_lshlrev_b32_e32 v14, 16, v0
	v_mov_b32_e32 v0, v15
	v_mov_b32_e32 v1, v12
	v_pk_mul_f32 v[0:1], v[0:1], v[20:21]
	v_mul_f32_e32 v13, v11, v10
	v_fma_f32 v2, v11, v10, v1
	v_add_f32_e32 v2, v0, v2
	v_div_scale_f32 v10, s[14:15], v2, v2, 1.0
	v_rcp_f32_e32 v11, v10
	s_nop 0
	v_fma_f32 v12, -v10, v11, 1.0
	v_fmac_f32_e32 v11, v12, v11
	v_div_scale_f32 v12, vcc, 1.0, v2, 1.0
	v_mul_f32_e32 v15, v12, v11
	v_fma_f32 v20, -v10, v15, v12
	v_fmac_f32_e32 v15, v20, v11
	v_fma_f32 v10, -v10, v15, v12
	v_div_fmas_f32 v10, v10, v11, v15
	v_div_fixup_f32 v2, v10, v2, 1.0
	v_pk_mul_f32 v[10:11], v[0:1], v[2:3] op_sel_hi:[1,0]
	s_waitcnt vmcnt(1)
	v_lshlrev_b32_e32 v0, 16, v4
	v_lshlrev_b32_e32 v1, 16, v16
	v_mul_f32_e32 v15, v13, v2
	v_pk_mul_f32 v[0:1], v[10:11], v[0:1]
	v_lshlrev_b32_e32 v12, 16, v5
	v_fma_f32 v1, v15, v14, v1
	v_add_f32_e32 v2, v0, v1
	v_and_b32_e32 v1, 0xffff0000, v16
	v_and_b32_e32 v0, 0xffff0000, v4
	v_pk_mul_f32 v[0:1], v[10:11], v[0:1]
	v_lshlrev_b32_e32 v13, 16, v17
	v_fma_f32 v1, v15, v22, v1
	v_pk_mul_f32 v[12:13], v[10:11], v[12:13]
	v_add_f32_e32 v0, v0, v1
	v_fma_f32 v1, v15, v23, v13
	v_add_f32_e32 v1, v12, v1
	v_and_b32_e32 v13, 0xffff0000, v17
	v_and_b32_e32 v12, 0xffff0000, v5
	v_pk_mul_f32 v[4:5], v[10:11], v[12:13]
	v_cvt_pk_bf16_f32 v0, v2, v0
	v_and_b32_e32 v3, 0xffff0000, v3
	v_fma_f32 v2, v15, v24, v5
	v_add_f32_e32 v2, v4, v2
	v_lshlrev_b32_e32 v4, 16, v6
	v_lshlrev_b32_e32 v5, 16, v18
	v_pk_mul_f32 v[4:5], v[10:11], v[4:5]
	v_cvt_pk_bf16_f32 v1, v1, v2
	s_nop 0
	v_fma_f32 v2, v15, v25, v5
	v_add_f32_e32 v2, v4, v2
	v_and_b32_e32 v5, 0xffff0000, v18
	v_and_b32_e32 v4, 0xffff0000, v6
	v_pk_mul_f32 v[4:5], v[10:11], v[4:5]
	s_nop 0
	v_fma_f32 v5, v15, v26, v5
	v_add_f32_e32 v4, v4, v5
	v_cvt_pk_bf16_f32 v2, v2, v4
	v_lshlrev_b32_e32 v4, 16, v7
	v_lshlrev_b32_e32 v5, 16, v19
	v_pk_mul_f32 v[4:5], v[10:11], v[4:5]
	s_nop 0
	v_fma_f32 v5, v15, v27, v5
	v_add_f32_e32 v6, v4, v5
	v_and_b32_e32 v5, 0xffff0000, v19
	v_and_b32_e32 v4, 0xffff0000, v7
	v_pk_mul_f32 v[4:5], v[10:11], v[4:5]
	s_nop 0
	v_fma_f32 v3, v15, v3, v5
	v_add_f32_e32 v3, v4, v3
	v_lshlrev_b64 v[4:5], 11, v[8:9]
	v_lshl_add_u64 v[4:5], s[84:85], 0, v[4:5]
	v_lshl_add_u64 v[4:5], v[4:5], 0, s[16:17]
	v_lshl_add_u64 v[4:5], v[4:5], 0, v[144:145]
	v_cvt_pk_bf16_f32 v3, v6, v3
	global_store_dwordx4 v[4:5], v[0:3], off offset:512
	s_cbranch_scc1 .LBB0_902
; template <bool MERGE> __device__ __forceinline__ void compute_b(LAS unsigned char* lds, const UD& x, unsigned char* ws, unsigned char* dout, int wid, int lane, const u32x4 (&pw)[10], float mx, float lsum) {
;     ...
;         if (x.h < 4) {
;             const int g = x.h, hw = 1 << g;
;             const bf16_t* VP = (const bf16_t*)(ws + off_vp(x.b));
; #pragma unroll 1
;             for (int p = 0; p < 8; ++p) {
;                 const int s = t0 + 4 * p + (lane >> 4);
;                 const bf16_t* base = VP + tokb * PWD + g * 64 + 4 * (lane & 15);
	s_bfe_u32 s14, s45, 0x30008
	s_lshl_b32 s18, s14, 17
	s_lshl_b32 s19, s14, 8
	s_lshl_b32 s20, -1, s22
	s_mul_i32 s15, s0, 0xa00000
	v_readlane_b32 s24, v252, 1
	s_mul_hi_i32 s14, s0, 0xa00000
	v_readlane_b32 s25, v252, 2
	s_add_u32 s21, s24, s15
	s_addc_u32 s23, s25, s14
	s_lshl_b64 s[14:15], s[0:1], 20
	s_add_u32 s14, s21, s14
	s_addc_u32 s15, s23, s15
	s_add_u32 s14, s14, s16
	s_addc_u32 s15, s15, s17
	v_add_u32_e32 v0, s19, v212
	s_cmp_lg_u32 s22, 0
	v_ashrrev_i32_e32 v1, 31, v0
	v_mov_b32_e32 v147, v81
	s_cselect_b64 s[46:47], -1, 0
	s_cmp_gt_u32 s22, 1
	v_lshlrev_b64 v[4:5], 11, v[0:1]
	v_lshlrev_b64 v[6:7], 9, v[0:1]
	v_lshl_add_u64 v[0:1], s[14:15], 0, v[146:147]
	s_mov_b64 s[14:15], 0xc400000
	s_cselect_b64 s[54:55], -1, 0
	s_cmp_gt_u32 s22, 2
	v_lshl_add_u64 v[0:1], v[0:1], 0, s[14:15]
	s_cselect_b64 s[56:57], -1, 0
	s_lshl_b32 s14, s20, 9
	s_add_i32 s14, s14, s18
	v_add_u32_e32 v2, s14, v211
	s_add_i32 s19, s19, s20
	s_lshl_b64 s[14:15], s[0:1], 22
	s_add_u32 s14, s16, s14
	s_addc_u32 s15, s17, s15
	s_mul_hi_i32 s1, s0, 0xb00000
	s_mul_i32 s0, s0, 0xb00000
	s_add_u32 s0, s16, s0
	s_addc_u32 s1, s17, s1
	v_lshl_add_u64 v[4:5], s[14:15], 0, v[4:5]
	v_lshl_add_u64 v[6:7], s[0:1], 0, v[6:7]
	v_add_u32_e32 v3, s19, v213
	v_lshl_add_u64 v[4:5], v[138:139], 0, v[4:5]
	v_lshl_add_u64 v[6:7], v[140:141], 0, v[6:7]
	s_mov_b64 s[58:59], 0
	v_mbcnt_lo_u32_b32 v232, -1, 0
	v_mbcnt_hi_u32_b32 v232, -1, v232
	v_lshrrev_b32_e32 v233, 3, v232
	v_lshrrev_b32_e32 v234, 4, v232
	v_sub_u32_e32 v233, v233, v234
	v_and_b32_e32 v234, 7, v232
	v_and_b32_e32 v235, 15, v232
	v_lshlrev_b32_e32 v234, 4, v234
	v_lshlrev_b32_e32 v235, 3, v235
	v_sub_u32_e32 v234, v234, v235
	v_lshl_add_u32 v235, v233, 9, v234
	v_lshl_add_u32 v233, v233, 11, v234
	v_ashrrev_i32_e32 v234, 31, v235
	v_add_co_u32_e32 v76, vcc, v6, v235
	v_addc_co_u32_e32 v77, vcc, v7, v234, vcc
	v_ashrrev_i32_e32 v234, 31, v233
	v_add_co_u32_e32 v78, vcc, v4, v233
	v_addc_co_u32_e32 v79, vcc, v5, v234, vcc
	v_readfirstlane_b32 s98, v3
	s_sub_i32 s98, s98, s20
	s_add_i32 s98, s98, -15
	s_mov_b32 s99, 0
	s_branch .Lpl_fast

; template <bool MERGE> __device__ __forceinline__ void compute_b(LAS unsigned char* lds, const UD& x, unsigned char* ws, unsigned char* dout, int wid, int lane, const u32x4 (&pw)[10], float mx, float lsum) {
;     ...
;             for (int p = 0; p < 8; ++p) {
;                 const int s = t0 + 4 * p + (lane >> 4);
;                 const bf16_t* base = VP + tokb * PWD + g * 64 + 4 * (lane & 15);
;                 float s0 = 0.f, s1 = 0.f, s2 = 0.f, s3 = 0.f; int cnt = 0;
;                 const u32x2 me = *(const u32x2*)(base + (size_t)s * PWD);
; #pragma unroll
;                 for (int j0 = 0; j0 < 16; j0 += 8) {
;                     if (j0 < 2 * hw) {
;                         u32x2 vv[8];
; #pragma unroll
;                         for (int jj = 0; jj < 8; ++jj) { const int j = s - hw + j0 + jj; const bool ok = (j0 + jj < 2 * hw) && (j >= 0) && (j < SEQ);
;                             vv[jj] = (u32x2){0u, 0u}; if (ok) vv[jj] = *(const u32x2*)(base + (size_t)j * PWD); cnt += ok ? 1 : 0; }
.Lpl_fast:
	s_mov_b32 s101, 0.5
	s_cmp_lg_u64 s[46:47], 0
	s_cselect_b32 s101, 0x3e800000, s101
	s_cmp_lg_u64 s[54:55], 0
	s_cselect_b32 s101, 0x3e000000, s101
	s_cmp_lg_u64 s[56:57], 0
	s_cselect_b32 s101, 0x3d800000, s101
	v_mbcnt_lo_u32_b32 v7, -1, 0
	v_mbcnt_hi_u32_b32 v7, -1, v7
	v_lshrrev_b32_e32 v7, 3, v7
	v_mov_b32_e32 v4, 1
	v_cndmask_b32_e64 v4, v4, 2, s[46:47]
	v_cndmask_b32_e64 v4, v4, 4, s[54:55]
	v_cndmask_b32_e64 v4, v4, 8, s[56:57]
	v_min_u32_e32 v5, v4, v7
	v_sub_u32_e32 v6, 8, v7
	v_min_u32_e32 v6, v4, v6
	v_mov_b64_e32 v[12:13], 0
	v_mov_b64_e32 v[14:15], 0
	v_mov_b64_e32 v[16:17], 0
	v_mov_b64_e32 v[18:19], 0
	v_mov_b64_e32 v[20:21], 0
	v_mov_b64_e32 v[22:23], 0
	v_mov_b64_e32 v[24:25], 0
	v_mov_b64_e32 v[26:27], 0
	v_mov_b64_e32 v[28:29], 0
	v_mov_b64_e32 v[30:31], 0
	v_mov_b64_e32 v[32:33], 0
	v_mov_b64_e32 v[34:35], 0
	v_mov_b64_e32 v[36:37], 0
	v_mov_b64_e32 v[38:39], 0
	v_mov_b64_e32 v[40:41], 0
	v_mov_b64_e32 v[42:43], 0
	v_mov_b64_e32 v[44:45], 0
	v_mov_b64_e32 v[46:47], 0
	v_mov_b64_e32 v[48:49], 0
	v_mov_b64_e32 v[50:51], 0
	v_mov_b64_e32 v[52:53], 0
	v_mov_b64_e32 v[54:55], 0
	v_mov_b64_e32 v[56:57], 0
	v_mov_b64_e32 v[58:59], 0
	v_mov_b64_e32 v[60:61], 0
	v_mov_b64_e32 v[62:63], 0
	v_mov_b64_e32 v[64:65], 0
	v_mov_b64_e32 v[66:67], 0
	v_mov_b64_e32 v[68:69], 0
	v_mov_b64_e32 v[70:71], 0
	v_mov_b64_e32 v[72:73], 0
	v_mov_b64_e32 v[74:75], 0

; template <bool MERGE> __device__ __forceinline__ void compute_b(LAS unsigned char* lds, const UD& x, unsigned char* ws, unsigned char* dout, int wid, int lane, const u32x4 (&pw)[10], float mx, float lsum) {
;     ...
;                 for (int j0 = 0; j0 < 16; j0 += 8) {
;                     if (j0 < 2 * hw) {
;                         u32x2 vv[8];
; #pragma unroll
;                         for (int jj = 0; jj < 8; ++jj) { const int j = s - hw + j0 + jj; const bool ok = (j0 + jj < 2 * hw) && (j >= 0) && (j < SEQ);
;                             vv[jj] = (u32x2){0u, 0u}; if (ok) vv[jj] = *(const u32x2*)(base + (size_t)j * PWD); cnt += ok ? 1 : 0; }
; #pragma unroll
;                         for (int jj = 0; jj < 8; ++jj) { s0 += __uint_as_float(vv[jj].x << 16); s1 += __uint_as_float(vv[jj].x & 0xffff0000u); s2 += __uint_as_float(vv[jj].y << 16); s3 += __uint_as_float(vv[jj].y & 0xffff0000u); }
;                     }
;                 }
;                 const float rc = 1.0f / (float)cnt;
.Lpl_ld_done:
	v_mov_b64_e32 v[242:243], 0
	v_mov_b64_e32 v[244:245], 0
	v_mov_b64_e32 v[246:247], 0
	v_mov_b64_e32 v[248:249], 0
	s_lshl_b32 s100, s99, 3
	s_add_i32 s100, s100, s98
	v_mov_b32_e32 v196, s101
	s_waitcnt vmcnt(0)
	s_cmp_eq_u32 s100, 0
	s_cbranch_scc1 .Lpl_mask_lo
	s_cmpk_eq_u32 s100, 0x7f8
	s_cbranch_scc1 .Lpl_mask_hi
	s_branch .Lpl_sum
.Lpl_mask_lo:
	v_cmp_le_u32_e32 vcc, 8, v5
	v_cndmask_b32_e32 v12, 0, v12, vcc
	v_cndmask_b32_e32 v13, 0, v13, vcc
	v_cndmask_b32_e32 v14, 0, v14, vcc
	v_cndmask_b32_e32 v15, 0, v15, vcc
	v_cmp_le_u32_e32 vcc, 7, v5
	v_cndmask_b32_e32 v16, 0, v16, vcc
	v_cndmask_b32_e32 v17, 0, v17, vcc
	v_cndmask_b32_e32 v18, 0, v18, vcc
	v_cndmask_b32_e32 v19, 0, v19, vcc
	v_cmp_le_u32_e32 vcc, 6, v5
	v_cndmask_b32_e32 v20, 0, v20, vcc
	v_cndmask_b32_e32 v21, 0, v21, vcc
	v_cndmask_b32_e32 v22, 0, v22, vcc
	v_cndmask_b32_e32 v23, 0, v23, vcc
	v_cmp_le_u32_e32 vcc, 5, v5
	v_cndmask_b32_e32 v24, 0, v24, vcc
	v_cndmask_b32_e32 v25, 0, v25, vcc
	v_cndmask_b32_e32 v26, 0, v26, vcc
	v_cndmask_b32_e32 v27, 0, v27, vcc
	v_cmp_le_u32_e32 vcc, 4, v5
	v_cndmask_b32_e32 v28, 0, v28, vcc
	v_cndmask_b32_e32 v29, 0, v29, vcc
	v_cndmask_b32_e32 v30, 0, v30, vcc
	v_cndmask_b32_e32 v31, 0, v31, vcc
	v_cmp_le_u32_e32 vcc, 3, v5
	v_cndmask_b32_e32 v32, 0, v32, vcc
	v_cndmask_b32_e32 v33, 0, v33, vcc
	v_cndmask_b32_e32 v34, 0, v34, vcc
	v_cndmask_b32_e32 v35, 0, v35, vcc
	v_cmp_le_u32_e32 vcc, 2, v5
	v_cndmask_b32_e32 v36, 0, v36, vcc
	v_cndmask_b32_e32 v37, 0, v37, vcc
	v_cndmask_b32_e32 v38, 0, v38, vcc
	v_cndmask_b32_e32 v39, 0, v39, vcc
	v_cmp_le_u32_e32 vcc, 1, v5
	v_cndmask_b32_e32 v40, 0, v40, vcc
	v_cndmask_b32_e32 v41, 0, v41, vcc
	v_cndmask_b32_e32 v42, 0, v42, vcc
	v_cndmask_b32_e32 v43, 0, v43, vcc
	v_add_u32_e32 v197, v4, v5
	v_cvt_f32_u32_e32 v197, v197
	v_div_scale_f32 v198, s[0:1], v197, v197, 1.0
	v_rcp_f32_e32 v199, v198
	s_nop 0
	v_fma_f32 v232, -v198, v199, 1.0
	v_fmac_f32_e32 v199, v232, v199
	v_div_scale_f32 v232, vcc, 1.0, v197, 1.0
	v_mul_f32_e32 v233, v232, v199
	v_fma_f32 v234, -v198, v233, v232
	v_fmac_f32_e32 v233, v234, v199
	v_fma_f32 v198, -v198, v233, v232
	v_div_fmas_f32 v198, v198, v199, v233
	v_div_fixup_f32 v196, v198, v197, 1.0
	s_branch .Lpl_sum
.Lpl_mask_hi:
	v_cmp_lt_u32_e32 vcc, 0, v6
	v_cndmask_b32_e32 v44, 0, v44, vcc
	v_cndmask_b32_e32 v45, 0, v45, vcc
	v_cndmask_b32_e32 v46, 0, v46, vcc
	v_cndmask_b32_e32 v47, 0, v47, vcc
	v_cmp_lt_u32_e32 vcc, 1, v6
	v_cndmask_b32_e32 v48, 0, v48, vcc
	v_cndmask_b32_e32 v49, 0, v49, vcc
	v_cndmask_b32_e32 v50, 0, v50, vcc
	v_cndmask_b32_e32 v51, 0, v51, vcc
	v_cmp_lt_u32_e32 vcc, 2, v6
	v_cndmask_b32_e32 v52, 0, v52, vcc
	v_cndmask_b32_e32 v53, 0, v53, vcc
	v_cndmask_b32_e32 v54, 0, v54, vcc
	v_cndmask_b32_e32 v55, 0, v55, vcc
	v_cmp_lt_u32_e32 vcc, 3, v6
	v_cndmask_b32_e32 v56, 0, v56, vcc
	v_cndmask_b32_e32 v57, 0, v57, vcc
	v_cndmask_b32_e32 v58, 0, v58, vcc
	v_cndmask_b32_e32 v59, 0, v59, vcc
	v_cmp_lt_u32_e32 vcc, 4, v6
	v_cndmask_b32_e32 v60, 0, v60, vcc
	v_cndmask_b32_e32 v61, 0, v61, vcc
	v_cndmask_b32_e32 v62, 0, v62, vcc
	v_cndmask_b32_e32 v63, 0, v63, vcc
	v_cmp_lt_u32_e32 vcc, 5, v6
	v_cndmask_b32_e32 v64, 0, v64, vcc
	v_cndmask_b32_e32 v65, 0, v65, vcc
	v_cndmask_b32_e32 v66, 0, v66, vcc
	v_cndmask_b32_e32 v67, 0, v67, vcc
	v_cmp_lt_u32_e32 vcc, 6, v6
	v_cndmask_b32_e32 v68, 0, v68, vcc
	v_cndmask_b32_e32 v69, 0, v69, vcc
	v_cndmask_b32_e32 v70, 0, v70, vcc
	v_cndmask_b32_e32 v71, 0, v71, vcc
	v_cmp_lt_u32_e32 vcc, 7, v6
	v_cndmask_b32_e32 v72, 0, v72, vcc
	v_cndmask_b32_e32 v73, 0, v73, vcc
	v_cndmask_b32_e32 v74, 0, v74, vcc
	v_cndmask_b32_e32 v75, 0, v75, vcc
	v_add_u32_e32 v197, v4, v6
	v_cvt_f32_u32_e32 v197, v197
	v_div_scale_f32 v198, s[0:1], v197, v197, 1.0
	v_rcp_f32_e32 v199, v198
	s_nop 0
	v_fma_f32 v232, -v198, v199, 1.0
	v_fmac_f32_e32 v199, v232, v199
	v_div_scale_f32 v232, vcc, 1.0, v197, 1.0
	v_mul_f32_e32 v233, v232, v199
	v_fma_f32 v234, -v198, v233, v232
	v_fmac_f32_e32 v233, v234, v199
	v_fma_f32 v198, -v198, v233, v232
	v_div_fmas_f32 v198, v198, v199, v233
	v_div_fixup_f32 v196, v198, v197, 1.0
.Lpl_sum:
	s_cmp_lg_u64 s[56:57], 0
	s_cbranch_scc0 .Lpl_s1
	v_lshlrev_b32_e32 v232, 16, v12
	v_and_b32_e32 v233, 0xffff0000, v12
	v_pk_add_f32 v[242:243], v[242:243], v[232:233]
	v_lshlrev_b32_e32 v234, 16, v13
	v_and_b32_e32 v235, 0xffff0000, v13
	v_pk_add_f32 v[244:245], v[244:245], v[234:235]
	v_lshlrev_b32_e32 v232, 16, v14
	v_and_b32_e32 v233, 0xffff0000, v14
	v_pk_add_f32 v[246:247], v[246:247], v[232:233]
	v_lshlrev_b32_e32 v234, 16, v15
	v_and_b32_e32 v235, 0xffff0000, v15
	v_pk_add_f32 v[248:249], v[248:249], v[234:235]
	v_lshlrev_b32_e32 v232, 16, v16
	v_and_b32_e32 v233, 0xffff0000, v16
	v_pk_add_f32 v[242:243], v[242:243], v[232:233]
	v_lshlrev_b32_e32 v234, 16, v17
	v_and_b32_e32 v235, 0xffff0000, v17
	v_pk_add_f32 v[244:245], v[244:245], v[234:235]
	v_lshlrev_b32_e32 v232, 16, v18
	v_and_b32_e32 v233, 0xffff0000, v18
	v_pk_add_f32 v[246:247], v[246:247], v[232:233]
	v_lshlrev_b32_e32 v234, 16, v19
	v_and_b32_e32 v235, 0xffff0000, v19
	v_pk_add_f32 v[248:249], v[248:249], v[234:235]
	v_lshlrev_b32_e32 v232, 16, v20
	v_and_b32_e32 v233, 0xffff0000, v20
	v_pk_add_f32 v[242:243], v[242:243], v[232:233]
	v_lshlrev_b32_e32 v234, 16, v21
	v_and_b32_e32 v235, 0xffff0000, v21
	v_pk_add_f32 v[244:245], v[244:245], v[234:235]
	v_lshlrev_b32_e32 v232, 16, v22
	v_and_b32_e32 v233, 0xffff0000, v22
	v_pk_add_f32 v[246:247], v[246:247], v[232:233]
	v_lshlrev_b32_e32 v234, 16, v23
	v_and_b32_e32 v235, 0xffff0000, v23
	v_pk_add_f32 v[248:249], v[248:249], v[234:235]
	v_lshlrev_b32_e32 v232, 16, v24
	v_and_b32_e32 v233, 0xffff0000, v24
	v_pk_add_f32 v[242:243], v[242:243], v[232:233]
	v_lshlrev_b32_e32 v234, 16, v25
	v_and_b32_e32 v235, 0xffff0000, v25
	v_pk_add_f32 v[244:245], v[244:245], v[234:235]
	v_lshlrev_b32_e32 v232, 16, v26
	v_and_b32_e32 v233, 0xffff0000, v26
	v_pk_add_f32 v[246:247], v[246:247], v[232:233]
	v_lshlrev_b32_e32 v234, 16, v27
	v_and_b32_e32 v235, 0xffff0000, v27
	v_pk_add_f32 v[248:249], v[248:249], v[234:235]

; __device__ __forceinline__ unsigned cvt_pk_bf16(float lo, float hi) { unsigned r; asm volatile("v_cvt_pk_bf16_f32 %0, %1, %2" : "=v"(r) : "v"(lo), "v"(hi)); return r; }
; template <bool MERGE> __device__ __forceinline__ void compute_b(LAS unsigned char* lds, const UD& x, unsigned char* ws, unsigned char* dout, int wid, int lane, const u32x4 (&pw)[10], float mx, float lsum) {
;     ...
;                 const float rc = 1.0f / (float)cnt;
;                 u32x2 w2; w2.x = pg8::cvt_pk_bf16(s0 * rc - __uint_as_float(me.x << 16), s1 * rc - __uint_as_float(me.x & 0xffff0000u)); w2.y = pg8::cvt_pk_bf16(s2 * rc - __uint_as_float(me.y << 16), s3 * rc - __uint_as_float(me.y & 0xffff0000u));
;                 *(u32x2*)(MIX + (tokb + (size_t)s) * DM + g * 64 + 4 * (lane & 15)) = w2;
;             }
.Lpl_s6:
	v_lshlrev_b32_e32 v232, 16, v8
	v_and_b32_e32 v233, 0xffff0000, v8
	v_fma_f32 v234, v242, v196, -v232
	v_fma_f32 v235, v243, v196, -v233
	v_cvt_pk_bf16_f32 v8, v234, v235
	v_lshlrev_b32_e32 v232, 16, v9
	v_and_b32_e32 v233, 0xffff0000, v9
	v_fma_f32 v234, v244, v196, -v232
	v_fma_f32 v235, v245, v196, -v233
	v_cvt_pk_bf16_f32 v9, v234, v235
	v_lshlrev_b32_e32 v232, 16, v10
	v_and_b32_e32 v233, 0xffff0000, v10
	v_fma_f32 v234, v246, v196, -v232
	v_fma_f32 v235, v247, v196, -v233
	v_cvt_pk_bf16_f32 v10, v234, v235
	v_lshlrev_b32_e32 v232, 16, v11
	v_and_b32_e32 v233, 0xffff0000, v11
	v_fma_f32 v234, v248, v196, -v232
	v_fma_f32 v235, v249, v196, -v233
	v_cvt_pk_bf16_f32 v11, v234, v235
	global_store_dwordx4 v[78:79], v[8:11], off
	v_add_co_u32_e32 v76, vcc, 0x1000, v76
	v_addc_co_u32_e32 v77, vcc, 0, v77, vcc
	v_add_co_u32_e32 v78, vcc, 0x4000, v78
	v_addc_co_u32_e32 v79, vcc, 0, v79, vcc
	s_add_i32 s99, s99, 1
	s_cmp_lt_u32 s99, 4
	s_cbranch_scc1 .Lpl_pass
	s_branch .LBB0_902
